# deferred phase-0 work now only in the two idle GEMM tails (A-in tail: b_w_in, w_q, w_k transposes; B-in tail: w_v, b_w_out transposes + gate folding); nothing after the A-out unit
# baseline (speedup 1.0000x reference)
.LBB0_232:
	s_cmp_lt_u32 s2, 0x80
	s_cbranch_scc1 .Lp1_resume
	s_mov_b32 s98, 3
	s_mov_b32 s70, 0x1000
	s_mov_b32 s71, 0x2c00
	s_mov_b32 s72, 0x400
	s_mov_b32 s73, 0x0
	s_mov_b32 s74, 0x0
	s_mov_b32 s75, 0x2bff
	s_lshl_b32 s76, s70, 5
	s_lshl_b32 s77, s70, 7
	s_lshl_b32 s78, s70, 6
	s_lshl_b32 s79, s70, 1
	s_branch .Lp0_entry

.LBB0_354:
.Lp3_resume:
	s_mov_b64 s[6:7], s[96:97]
	s_waitcnt vmcnt(0)
	v_mov_b32_e32 v0, v201
	s_waitcnt lgkmcnt(0)
	s_barrier
	s_nop 0
	v_cmp_eq_u32_e32 vcc, 0, v0
	s_and_saveexec_b64 s[38:39], vcc
	s_cbranch_execz .LBB0_398
	s_add_i32 s1, 0, 0x25fc0
	v_mov_b32_e32 v0, s1
	s_load_dwordx2 s[40:41], s[6:7], 0xc0
	s_getreg_b32 s0, hwreg(HW_REG_XCC_ID, 0, 4)
	s_waitcnt vmcnt(0) expcnt(0) lgkmcnt(0)
	ds_read_b32 v2, v0
	s_add_i32 s1, 0, 0x25fc4
	v_mov_b32_e32 v0, s1
	ds_read_b32 v0, v0
	s_and_b32 s0, s0, 15
	s_waitcnt lgkmcnt(1)
	v_cmp_ne_u32_e32 vcc, 0, v2
	s_cbranch_vccnz .LBB0_369
	s_add_u32 s6, s40, 0x44752200
	s_addc_u32 s7, s41, 0
	s_add_u32 s4, s40, 0x44752400
	s_addc_u32 s5, s41, 0
	s_add_u32 s10, s40, 0x44752500
	s_addc_u32 s11, s41, 0
	s_add_u32 s12, s40, 0x44752600
	s_addc_u32 s13, s41, 0
	s_add_u32 s14, s40, 0x44752700
	s_addc_u32 s15, s41, 0
	s_add_u32 s16, s40, 0x44752800
	s_addc_u32 s17, s41, 0
	s_add_u32 s18, s40, 0x44752900
	s_addc_u32 s19, s41, 0
	s_add_u32 s20, s40, 0x44752a00
	s_addc_u32 s21, s41, 0
	s_add_u32 s22, s40, 0x44752b00
	s_addc_u32 s23, s41, 0
	s_add_u32 s24, s40, 0x44752c00
	s_addc_u32 s25, s41, 0
	s_add_u32 s26, s40, 0x44752d00
	s_addc_u32 s27, s41, 0
	s_add_u32 s28, s40, 0x44752e00
	s_addc_u32 s29, s41, 0
	s_add_u32 s30, s40, 0x44752f00
	s_addc_u32 s31, s41, 0
	s_add_u32 s34, s40, 0x44753000
	s_addc_u32 s35, s41, 0
	s_add_u32 s36, s40, 0x44753100
	s_addc_u32 s37, s41, 0
	s_add_u32 s42, s40, 0x44753200
	s_addc_u32 s43, s41, 0
	s_add_u32 s44, s40, 0x44753300
	s_addc_u32 s45, s41, 0
	s_mov_b32 s1, 1
	s_mov_b64 s[8:9], 0
	s_waitcnt lgkmcnt(0)
	v_mov_b64_e32 v[0:1], s[4:5]
	v_mov_b64_e32 v[2:3], s[10:11]
	v_mov_b64_e32 v[4:5], s[12:13]
	v_mov_b64_e32 v[6:7], s[14:15]
	v_mov_b64_e32 v[8:9], s[16:17]
	v_mov_b64_e32 v[10:11], s[18:19]
	v_mov_b64_e32 v[12:13], s[20:21]
	v_mov_b64_e32 v[14:15], s[22:23]
	v_mov_b64_e32 v[16:17], s[24:25]
	v_mov_b64_e32 v[18:19], s[26:27]
	v_mov_b64_e32 v[20:21], s[28:29]
	v_mov_b64_e32 v[22:23], s[30:31]
	v_mov_b64_e32 v[24:25], s[34:35]
	v_mov_b64_e32 v[26:27], s[36:37]
	v_mov_b64_e32 v[28:29], s[42:43]
	v_mov_b64_e32 v[30:31], s[44:45]
	s_branch .LBB0_359

.LBB0_540:
	s_cmp_lt_u32 s2, 0x40
	s_cbranch_scc1 .Lp4_resume
	s_mov_b32 s98, 2
	s_mov_b32 s70, 0x2a00
	s_mov_b32 s71, 0x3800
	s_mov_b32 s72, 0x600
	s_mov_b32 s73, 0x2c00
	s_mov_b32 s74, 0x1000
	s_mov_b32 s75, 0x37ff
	s_lshl_b32 s76, s70, 5
	s_lshl_b32 s77, s70, 7
	s_lshl_b32 s78, s70, 6
	s_lshl_b32 s79, s70, 1
	s_branch .Lp0_entry
